# P10 x (f32) loads default policy instead of nt, on top of v111
# speedup vs baseline: 1.0101x; 1.0036x over previous
.LBB0_1035:
	s_ashr_i32 s5, s4, 31
	s_lshl_b64 s[0:1], s[4:5], 6
	s_waitcnt vmcnt(12)
	v_lshl_add_u64 v[32:33], v[52:53], 0, s[0:1]
	s_waitcnt lgkmcnt(0)
	global_load_dwordx4 v[88:91], v[32:33], off
	v_lshl_add_u64 v[32:33], v[54:55], 0, s[0:1]
	global_load_dwordx4 v[92:95], v[32:33], off
	s_add_i32 s6, s12, s4
	s_cmp_lt_i32 s6, 0x8000
	s_cselect_b32 s0, s6, s4
	s_ashr_i32 s1, s0, 31
	s_lshl_b64 s[2:3], s[0:1], 6
	v_lshl_add_u64 v[32:33], v[52:53], 0, s[2:3]
	global_load_dwordx4 v[96:99], v[32:33], off
	v_lshl_add_u64 v[32:33], v[54:55], 0, s[2:3]
	global_load_dwordx4 v[100:103], v[32:33], off
	s_lshl_b64 s[8:9], s[4:5], 12
	s_lshl_b64 s[2:3], s[4:5], 11
	v_lshl_add_u64 v[36:37], v[56:57], 0, s[8:9]
	v_lshl_add_u64 v[32:33], v[60:61], 0, s[2:3]
	v_lshl_add_u64 v[34:35], v[58:59], 0, s[2:3]
	global_load_dwordx4 v[48:51], v[36:37], off offset:3072
	global_load_dwordx4 v[104:107], v[36:37], off offset:2048
	global_load_dwordx2 v[80:81], v[32:33], off offset:1536 nt
	global_load_dwordx2 v[116:117], v[32:33], off offset:1024 nt
	global_load_dwordx2 v[118:119], v[32:33], off offset:512 nt
	global_load_dwordx2 v[120:121], v[32:33], off nt
	global_load_dwordx2 v[82:83], v[34:35], off offset:1536 nt
	global_load_dwordx2 v[122:123], v[34:35], off offset:1024 nt
	global_load_dwordx2 v[124:125], v[34:35], off offset:512 nt
	global_load_dwordx2 v[126:127], v[34:35], off nt
	global_load_dwordx4 v[108:111], v[36:37], off offset:1024
	global_load_dwordx4 v[112:115], v[36:37], off
	s_lshl_b64 s[2:3], s[0:1], 12
	s_lshl_b64 s[0:1], s[0:1], 11
	s_waitcnt vmcnt(20)
	v_lshl_add_u64 v[64:65], v[56:57], 0, s[2:3]
	v_lshl_add_u64 v[68:69], v[58:59], 0, s[0:1]
	v_lshl_add_u64 v[128:129], v[60:61], 0, s[0:1]
	global_load_dwordx4 v[44:47], v[64:65], off
	global_load_dwordx4 v[40:43], v[64:65], off offset:1024
	global_load_dwordx4 v[36:39], v[64:65], off offset:2048
	global_load_dwordx4 v[32:35], v[64:65], off offset:3072
	global_load_dwordx2 v[78:79], v[68:69], off nt
	global_load_dwordx2 v[74:75], v[68:69], off offset:512 nt
	global_load_dwordx2 v[70:71], v[68:69], off offset:1024 nt
	global_load_dwordx2 v[66:67], v[68:69], off offset:1536 nt
	global_load_dwordx2 v[76:77], v[128:129], off nt
	global_load_dwordx2 v[72:73], v[128:129], off offset:512 nt
	s_nop 0
	global_load_dwordx2 v[68:69], v[128:129], off offset:1024 nt
	global_load_dwordx2 v[64:65], v[128:129], off offset:1536 nt
	s_cmpk_gt_i32 s6, 0x7fff
	s_waitcnt vmcnt(27)
	v_mov_b32_e32 v128, v89
	v_mov_b32_e32 v129, v90
	v_mov_b32_e32 v89, v91
	s_waitcnt vmcnt(26)
	v_mov_b32_e32 v90, v93
	v_mov_b32_e32 v91, v94
	v_mov_b32_e32 v93, v95
	v_pk_add_f32 v[88:89], v[128:129], v[88:89]
	v_pk_add_f32 v[90:91], v[90:91], v[92:93]
	v_add_f32_e32 v88, v88, v89
	v_add_f32_e32 v89, v90, v91
	ds_bpermute_b32 v91, v84, v89
	ds_bpermute_b32 v90, v84, v88
	s_waitcnt vmcnt(25)
	v_add_f32_e32 v92, v96, v97
	v_add_f32_e32 v93, v98, v99
	s_waitcnt vmcnt(24)
	v_add_f32_e32 v94, v100, v101
	s_waitcnt lgkmcnt(1)
	v_add_f32_e32 v91, v89, v91
	v_add_f32_e32 v95, v102, v103
	v_add_f32_e32 v92, v92, v93
	s_waitcnt lgkmcnt(0)
	v_add_f32_e32 v96, v88, v90
	ds_bpermute_b32 v97, v85, v91
	v_add_f32_e32 v93, v94, v95
	ds_bpermute_b32 v94, v84, v92
	ds_bpermute_b32 v98, v85, v96
	ds_bpermute_b32 v95, v84, v93
	s_waitcnt lgkmcnt(3)
	v_add_f32_e32 v91, v91, v97
	v_fmamk_f32 v91, v91, 0x3a800000, v86
	s_waitcnt lgkmcnt(2)
	v_add_f32_e32 v88, v92, v94
	s_waitcnt lgkmcnt(1)
	v_add_f32_e32 v92, v96, v98
	s_waitcnt lgkmcnt(0)
	v_add_f32_e32 v90, v93, v95
	v_fmamk_f32 v92, v92, 0x3a800000, v86
	v_mul_f32_e32 v93, 0x4f800000, v91
	v_cmp_gt_f32_e32 vcc, s11, v91
	v_mul_f32_e32 v94, 0x4f800000, v92
	v_cmp_gt_f32_e64 s[0:1], s11, v92
	v_cndmask_b32_e32 v93, v91, v93, vcc
	v_sqrt_f32_e32 v95, v93
	v_cndmask_b32_e64 v92, v92, v94, s[0:1]
	v_sqrt_f32_e32 v94, v92
	ds_bpermute_b32 v89, v85, v88
	v_add_u32_e32 v96, -1, v95
	v_fma_f32 v100, -v96, v95, v93
	v_add_u32_e32 v98, -1, v94
	v_add_u32_e32 v97, 1, v95
	v_fma_f32 v102, -v98, v94, v92
	v_cmp_ge_f32_e64 s[2:3], 0, v100
	v_add_u32_e32 v99, 1, v94
	v_fma_f32 v101, -v97, v95, v93
	v_cndmask_b32_e64 v95, v95, v96, s[2:3]
	v_cmp_ge_f32_e64 s[2:3], 0, v102
	v_fma_f32 v103, -v99, v94, v92
	s_waitcnt vmcnt(18)
	v_lshlrev_b32_e32 v102, 16, v121
	v_cndmask_b32_e64 v94, v94, v98, s[2:3]
	v_cmp_lt_f32_e64 s[2:3], 0, v101
	v_lshl_add_u64 v[100:101], v[62:63], 0, s[8:9]
	ds_bpermute_b32 v91, v85, v90
	v_cndmask_b32_e64 v95, v95, v97, s[2:3]
	v_mul_f32_e32 v96, 0x37800000, v95
	v_cndmask_b32_e32 v95, v95, v96, vcc
	v_cmp_class_f32_e32 vcc, v93, v87
	v_cmp_lt_f32_e64 s[2:3], 0, v103
	v_and_b32_e32 v103, 0xffff0000, v121
	v_cndmask_b32_e32 v93, v95, v93, vcc
	v_cndmask_b32_e64 v94, v94, v99, s[2:3]
	v_div_scale_f32 v95, s[2:3], v93, v93, 1.0
	v_rcp_f32_e32 v96, v95
	v_mul_f32_e32 v97, 0x37800000, v94
	v_cndmask_b32_e64 v94, v94, v97, s[0:1]
	v_div_scale_f32 v97, vcc, 1.0, v93, 1.0
	v_fma_f32 v98, -v95, v96, 1.0
	v_fmac_f32_e32 v96, v98, v96
	v_mul_f32_e32 v98, v97, v96
	v_cmp_class_f32_e64 s[0:1], v92, v87
	v_fma_f32 v99, -v95, v98, v97
	v_fmac_f32_e32 v98, v99, v96
	v_cndmask_b32_e64 v92, v94, v92, s[0:1]
	v_div_scale_f32 v94, s[0:1], v92, v92, 1.0
	v_fma_f32 v95, -v95, v98, v97
	v_rcp_f32_e32 v97, v94
	v_div_fmas_f32 v95, v95, v96, v98
	v_div_fixup_f32 v96, v95, v93, 1.0
	v_fma_f32 v93, -v94, v97, 1.0
	v_fmac_f32_e32 v97, v93, v97
	v_div_scale_f32 v93, vcc, 1.0, v92, 1.0
	v_mul_f32_e32 v95, v93, v97
	v_fma_f32 v98, -v94, v95, v93
	v_fmac_f32_e32 v95, v98, v97
	v_fma_f32 v93, -v94, v95, v93
	v_div_fmas_f32 v93, v93, v97, v95
	v_div_fixup_f32 v98, v93, v92, 1.0
	s_waitcnt vmcnt(14)
	v_lshlrev_b32_e32 v92, 16, v126
	v_and_b32_e32 v93, 0xffff0000, v126
	v_pk_mul_f32 v[92:93], v[98:99], v[92:93] op_sel_hi:[0,1]
	v_lshlrev_b32_e32 v94, 16, v120
	v_and_b32_e32 v95, 0xffff0000, v120
	s_waitcnt vmcnt(12)
	v_pk_fma_f32 v[92:93], v[28:29], v[92:93], v[112:113]
	v_pk_mul_f32 v[94:95], v[96:97], v[94:95] op_sel_hi:[0,1]
	v_pk_fma_f32 v[92:93], v[20:21], v[94:95], v[92:93]
	v_lshlrev_b32_e32 v94, 16, v127
	v_and_b32_e32 v95, 0xffff0000, v127
	v_pk_mul_f32 v[94:95], v[98:99], v[94:95] op_sel_hi:[0,1]
	v_pk_fma_f32 v[94:95], v[30:31], v[94:95], v[114:115]
	v_pk_mul_f32 v[102:103], v[96:97], v[102:103] op_sel_hi:[0,1]
	v_pk_fma_f32 v[94:95], v[22:23], v[102:103], v[94:95]
	global_store_dwordx4 v[100:101], v[92:95], off nt
	v_lshlrev_b32_e32 v102, 16, v119
	v_and_b32_e32 v103, 0xffff0000, v119
	v_lshlrev_b32_e32 v92, 16, v124
	v_and_b32_e32 v93, 0xffff0000, v124
	v_pk_mul_f32 v[92:93], v[98:99], v[92:93] op_sel_hi:[0,1]
	v_lshlrev_b32_e32 v94, 16, v118
	v_and_b32_e32 v95, 0xffff0000, v118
	v_pk_fma_f32 v[92:93], v[24:25], v[92:93], v[108:109]
	v_pk_mul_f32 v[94:95], v[96:97], v[94:95] op_sel_hi:[0,1]
	v_pk_fma_f32 v[92:93], v[16:17], v[94:95], v[92:93]
	v_lshlrev_b32_e32 v94, 16, v125
	v_and_b32_e32 v95, 0xffff0000, v125
	v_pk_mul_f32 v[94:95], v[98:99], v[94:95] op_sel_hi:[0,1]
	v_pk_fma_f32 v[94:95], v[26:27], v[94:95], v[110:111]
	v_pk_mul_f32 v[102:103], v[96:97], v[102:103] op_sel_hi:[0,1]
	v_pk_fma_f32 v[94:95], v[18:19], v[102:103], v[94:95]
	global_store_dwordx4 v[100:101], v[92:95], off offset:1024 nt
	v_lshlrev_b32_e32 v102, 16, v117
	v_and_b32_e32 v103, 0xffff0000, v117
	v_lshlrev_b32_e32 v92, 16, v122
	v_and_b32_e32 v93, 0xffff0000, v122
	v_pk_mul_f32 v[92:93], v[98:99], v[92:93] op_sel_hi:[0,1]
	v_lshlrev_b32_e32 v94, 16, v116
	v_and_b32_e32 v95, 0xffff0000, v116
	v_pk_fma_f32 v[92:93], v[12:13], v[92:93], v[104:105]
	v_pk_mul_f32 v[94:95], v[96:97], v[94:95] op_sel_hi:[0,1]
	v_pk_fma_f32 v[92:93], v[4:5], v[94:95], v[92:93]
	v_lshlrev_b32_e32 v94, 16, v123
	v_and_b32_e32 v95, 0xffff0000, v123
	v_pk_mul_f32 v[94:95], v[98:99], v[94:95] op_sel_hi:[0,1]
	v_pk_fma_f32 v[94:95], v[14:15], v[94:95], v[106:107]
	v_pk_mul_f32 v[102:103], v[96:97], v[102:103] op_sel_hi:[0,1]
	v_pk_fma_f32 v[94:95], v[6:7], v[102:103], v[94:95]
	global_store_dwordx4 v[100:101], v[92:95], off offset:2048 nt
	s_nop 1
	v_lshlrev_b32_e32 v92, 16, v82
	v_and_b32_e32 v93, 0xffff0000, v82
	v_pk_mul_f32 v[92:93], v[98:99], v[92:93] op_sel_hi:[0,1]
	v_lshlrev_b32_e32 v82, 16, v83
	v_and_b32_e32 v83, 0xffff0000, v83
	v_pk_fma_f32 v[48:49], v[8:9], v[92:93], v[48:49]
	v_lshlrev_b32_e32 v92, 16, v80
	v_and_b32_e32 v93, 0xffff0000, v80
	v_pk_mul_f32 v[82:83], v[98:99], v[82:83] op_sel_hi:[0,1]
	v_lshlrev_b32_e32 v80, 16, v81
	v_and_b32_e32 v81, 0xffff0000, v81
	v_pk_mul_f32 v[92:93], v[96:97], v[92:93] op_sel_hi:[0,1]
	v_pk_fma_f32 v[50:51], v[10:11], v[82:83], v[50:51]
	v_pk_mul_f32 v[80:81], v[96:97], v[80:81] op_sel_hi:[0,1]
	v_pk_fma_f32 v[48:49], v[0:1], v[92:93], v[48:49]
	v_pk_fma_f32 v[50:51], v[2:3], v[80:81], v[50:51]
	global_store_dwordx4 v[100:101], v[48:51], off offset:3072 nt
	s_cbranch_scc1 .LBB0_1034
	s_waitcnt lgkmcnt(0)
	v_add_f32_e32 v48, v90, v91
	v_fmamk_f32 v48, v48, 0x3a800000, v86
	v_mul_f32_e32 v49, 0x4f800000, v48
	v_cmp_gt_f32_e32 vcc, s11, v48
	v_add_f32_e32 v81, v88, v89
	v_fmamk_f32 v81, v81, 0x3a800000, v86
	v_cndmask_b32_e32 v48, v48, v49, vcc
	v_sqrt_f32_e32 v49, v48
	v_mul_f32_e32 v82, 0x4f800000, v81
	s_ashr_i32 s7, s6, 31
	v_add_u32_e32 v50, -1, v49
	v_fma_f32 v80, -v50, v49, v48
	v_add_u32_e32 v51, 1, v49
	v_cmp_ge_f32_e64 s[0:1], 0, v80
	s_nop 1
	v_cndmask_b32_e64 v50, v49, v50, s[0:1]
	v_fma_f32 v49, -v51, v49, v48
	v_cmp_lt_f32_e64 s[0:1], 0, v49
	s_nop 1
	v_cndmask_b32_e64 v49, v50, v51, s[0:1]
	v_mul_f32_e32 v50, 0x37800000, v49
	v_cndmask_b32_e32 v49, v49, v50, vcc
	v_cmp_class_f32_e32 vcc, v48, v87
	s_nop 1
	v_cndmask_b32_e32 v48, v49, v48, vcc
	v_div_scale_f32 v49, s[0:1], v48, v48, 1.0
	v_rcp_f32_e32 v50, v49
	v_cmp_gt_f32_e64 s[0:1], s11, v81
	v_fma_f32 v51, -v49, v50, 1.0
	s_nop 0
	v_cndmask_b32_e64 v81, v81, v82, s[0:1]
	v_fmac_f32_e32 v50, v51, v50
	v_div_scale_f32 v51, vcc, 1.0, v48, 1.0
	v_sqrt_f32_e32 v82, v81
	v_mul_f32_e32 v80, v51, v50
	v_fma_f32 v83, -v49, v80, v51
	v_fmac_f32_e32 v80, v83, v50
	v_fma_f32 v49, -v49, v80, v51
	v_add_u32_e32 v51, -1, v82
	v_fma_f32 v83, -v51, v82, v81
	v_cmp_ge_f32_e64 s[2:3], 0, v83
	v_add_u32_e32 v83, 1, v82
	v_div_fmas_f32 v49, v49, v50, v80
	v_cndmask_b32_e64 v51, v82, v51, s[2:3]
	v_fma_f32 v82, -v83, v82, v81
	v_cmp_lt_f32_e64 s[2:3], 0, v82
	v_div_fixup_f32 v48, v49, v48, 1.0
	s_nop 0
	v_cndmask_b32_e64 v51, v51, v83, s[2:3]
	v_mul_f32_e32 v82, 0x37800000, v51
	v_cndmask_b32_e64 v51, v51, v82, s[0:1]
	v_cmp_class_f32_e64 s[0:1], v81, v87
	s_waitcnt vmcnt(11)
	v_and_b32_e32 v83, 0xffff0000, v78
	v_cndmask_b32_e64 v51, v51, v81, s[0:1]
	v_div_scale_f32 v81, s[0:1], v51, v51, 1.0
	v_rcp_f32_e32 v82, v81
	s_lshl_b64 s[0:1], s[6:7], 12
	v_fma_f32 v49, -v81, v82, 1.0
	v_fmac_f32_e32 v82, v49, v82
	v_div_scale_f32 v49, vcc, 1.0, v51, 1.0
	v_mul_f32_e32 v50, v49, v82
	v_fma_f32 v80, -v81, v50, v49
	v_fmac_f32_e32 v50, v80, v82
	v_fma_f32 v49, -v81, v50, v49
	v_div_fmas_f32 v49, v49, v82, v50
	v_div_fixup_f32 v50, v49, v51, 1.0
	v_lshlrev_b32_e32 v82, 16, v78
	v_pk_mul_f32 v[82:83], v[50:51], v[82:83] op_sel_hi:[0,1]
	v_lshlrev_b32_e32 v78, 16, v79
	v_and_b32_e32 v79, 0xffff0000, v79
	v_pk_fma_f32 v[44:45], v[28:29], v[82:83], v[44:45]
	s_waitcnt vmcnt(7)
	v_lshlrev_b32_e32 v82, 16, v76
	v_and_b32_e32 v83, 0xffff0000, v76
	v_pk_mul_f32 v[78:79], v[50:51], v[78:79] op_sel_hi:[0,1]
	v_lshlrev_b32_e32 v76, 16, v77
	v_and_b32_e32 v77, 0xffff0000, v77
	v_pk_mul_f32 v[82:83], v[48:49], v[82:83] op_sel_hi:[0,1]
	v_pk_fma_f32 v[46:47], v[30:31], v[78:79], v[46:47]
	v_pk_mul_f32 v[76:77], v[48:49], v[76:77] op_sel_hi:[0,1]
	v_lshl_add_u64 v[80:81], v[62:63], 0, s[0:1]
	v_pk_fma_f32 v[44:45], v[20:21], v[82:83], v[44:45]
	v_pk_fma_f32 v[46:47], v[22:23], v[76:77], v[46:47]
	global_store_dwordx4 v[80:81], v[44:47], off nt
	s_nop 1
	v_lshlrev_b32_e32 v44, 16, v74
	v_and_b32_e32 v45, 0xffff0000, v74
	v_pk_mul_f32 v[44:45], v[50:51], v[44:45] op_sel_hi:[0,1]
	v_pk_fma_f32 v[40:41], v[24:25], v[44:45], v[40:41]
	s_waitcnt vmcnt(7)
	v_lshlrev_b32_e32 v44, 16, v72
	v_and_b32_e32 v45, 0xffff0000, v72
	v_pk_mul_f32 v[44:45], v[48:49], v[44:45] op_sel_hi:[0,1]
	v_pk_fma_f32 v[40:41], v[16:17], v[44:45], v[40:41]
	v_lshlrev_b32_e32 v44, 16, v75
	v_and_b32_e32 v45, 0xffff0000, v75
	v_pk_mul_f32 v[44:45], v[50:51], v[44:45] op_sel_hi:[0,1]
	v_pk_fma_f32 v[42:43], v[26:27], v[44:45], v[42:43]
	v_lshlrev_b32_e32 v44, 16, v73
	v_and_b32_e32 v45, 0xffff0000, v73
	v_pk_mul_f32 v[44:45], v[48:49], v[44:45] op_sel_hi:[0,1]
	v_pk_fma_f32 v[42:43], v[18:19], v[44:45], v[42:43]
	global_store_dwordx4 v[80:81], v[40:43], off offset:1024 nt
	s_nop 1
	v_lshlrev_b32_e32 v40, 16, v70
	v_and_b32_e32 v41, 0xffff0000, v70
	v_pk_mul_f32 v[40:41], v[50:51], v[40:41] op_sel_hi:[0,1]
	v_pk_fma_f32 v[36:37], v[12:13], v[40:41], v[36:37]
	s_waitcnt vmcnt(7)
	v_lshlrev_b32_e32 v40, 16, v68
	v_and_b32_e32 v41, 0xffff0000, v68
	v_pk_mul_f32 v[40:41], v[48:49], v[40:41] op_sel_hi:[0,1]
	v_pk_fma_f32 v[36:37], v[4:5], v[40:41], v[36:37]
	v_lshlrev_b32_e32 v40, 16, v71
	v_and_b32_e32 v41, 0xffff0000, v71
	v_pk_mul_f32 v[40:41], v[50:51], v[40:41] op_sel_hi:[0,1]
	v_pk_fma_f32 v[38:39], v[14:15], v[40:41], v[38:39]
	v_lshlrev_b32_e32 v40, 16, v69
	v_and_b32_e32 v41, 0xffff0000, v69
	v_pk_mul_f32 v[40:41], v[48:49], v[40:41] op_sel_hi:[0,1]
	v_pk_fma_f32 v[38:39], v[6:7], v[40:41], v[38:39]
	global_store_dwordx4 v[80:81], v[36:39], off offset:2048 nt
	s_nop 1
	v_lshlrev_b32_e32 v36, 16, v66
	v_and_b32_e32 v37, 0xffff0000, v66
	v_pk_mul_f32 v[36:37], v[50:51], v[36:37] op_sel_hi:[0,1]
	v_pk_fma_f32 v[32:33], v[8:9], v[36:37], v[32:33]
	s_waitcnt vmcnt(7)
	v_lshlrev_b32_e32 v36, 16, v64
	v_and_b32_e32 v37, 0xffff0000, v64
	v_pk_mul_f32 v[36:37], v[48:49], v[36:37] op_sel_hi:[0,1]
	v_pk_fma_f32 v[32:33], v[0:1], v[36:37], v[32:33]
	v_lshlrev_b32_e32 v36, 16, v67
	v_and_b32_e32 v37, 0xffff0000, v67
	v_pk_mul_f32 v[36:37], v[50:51], v[36:37] op_sel_hi:[0,1]
	v_pk_fma_f32 v[34:35], v[10:11], v[36:37], v[34:35]
	v_lshlrev_b32_e32 v36, 16, v65
	v_and_b32_e32 v37, 0xffff0000, v65
	v_pk_mul_f32 v[36:37], v[48:49], v[36:37] op_sel_hi:[0,1]
	v_pk_fma_f32 v[34:35], v[2:3], v[36:37], v[34:35]
	global_store_dwordx4 v[80:81], v[32:35], off offset:3072 nt
	s_branch .LBB0_1034
